# attention kt loops: waves 4..7 enter 448 cycles late so the two waves of a SIMD do not run their exp and MFMA-only stretches in lockstep
# speedup vs baseline: 1.0075x; 1.0021x over previous
.Lfx_entry:
	v_readfirstlane_b32 s67, v195
	s_cmp_lt_u32 s67, 4
	s_cbranch_scc1 .Lfx_nostag
	s_sleep 7
